# attn64: second half-step's first K fragments read during the first half-step's P.V tail
# baseline (speedup 1.0000x reference)
.LBB0_946:
	s_mul_hi_u32 s6, s81, 0xcccccccd
	s_lshr_b32 s6, s6, 2
	s_mul_i32 s6, s6, 0x14000
	v_subrev_u32_e32 v16, s6, v215
	s_cmp_lg_u32 0, -1
	s_cselect_b32 s6, 0, 0
	v_add_u32_e32 v16, s6, v16
	ds_read_b64_tr_b16 v[116:117], v16 offset:0x1000
	ds_read_b64_tr_b16 v[118:119], v16 offset:0x1800
	ds_read_b64_tr_b16 v[120:121], v16 offset:0x1200
	ds_read_b64_tr_b16 v[122:123], v16 offset:0x1a00
	ds_read_b64_tr_b16 v[124:125], v16 offset:0x1400
	ds_read_b64_tr_b16 v[126:127], v16 offset:0x1c00
	ds_read_b64_tr_b16 v[128:129], v16 offset:0x1600
	ds_read_b64_tr_b16 v[130:131], v16 offset:0x1e00
	s_waitcnt lgkmcnt(8)
	s_nop 0
	v_mfma_f32_32x32x16_bf16 v[66:81], v[228:231], v[180:183], v[66:81]
	v_exp_f32_e32 v132, v132
	v_exp_f32_e32 v133, v133
	v_mfma_f32_32x32x16_bf16 v[50:65], v[232:235], v[180:183], v[50:65]
	v_exp_f32_e32 v134, v134
	v_exp_f32_e32 v135, v135
	v_mfma_f32_32x32x16_bf16 v[34:49], v[236:239], v[180:183], v[34:49]
	v_exp_f32_e32 v136, v136
	v_exp_f32_e32 v137, v137
	v_mfma_f32_32x32x16_bf16 v[18:33], v[240:243], v[180:183], v[18:33]
	v_exp_f32_e32 v138, v138
	v_exp_f32_e32 v139, v139
	ds_read_b64_tr_b16 v[100:101], v16 offset:0x2000
	ds_read_b64_tr_b16 v[102:103], v16 offset:0x2800
	ds_read_b64_tr_b16 v[104:105], v16 offset:0x2200
	ds_read_b64_tr_b16 v[106:107], v16 offset:0x2a00
	ds_read_b64_tr_b16 v[108:109], v16 offset:0x2400
	ds_read_b64_tr_b16 v[110:111], v16 offset:0x2c00
	ds_read_b64_tr_b16 v[112:113], v16 offset:0x2600
	ds_read_b64_tr_b16 v[114:115], v16 offset:0x2e00
	s_waitcnt lgkmcnt(8)
	v_mfma_f32_32x32x16_bf16 v[66:81], v[116:119], v[12:15], v[66:81]
	v_exp_f32_e32 v140, v140
	v_exp_f32_e32 v141, v141
	v_mfma_f32_32x32x16_bf16 v[50:65], v[120:123], v[12:15], v[50:65]
	v_exp_f32_e32 v142, v142
	v_exp_f32_e32 v143, v143
	v_mfma_f32_32x32x16_bf16 v[34:49], v[124:127], v[12:15], v[34:49]
	v_exp_f32_e32 v144, v144
	v_exp_f32_e32 v145, v145
	v_mfma_f32_32x32x16_bf16 v[18:33], v[128:131], v[12:15], v[18:33]
	v_exp_f32_e32 v146, v146
	v_exp_f32_e32 v147, v147
	ds_read_b64_tr_b16 v[12:13], v16 offset:0x3000
	ds_read_b64_tr_b16 v[14:15], v16 offset:0x3800
	ds_read_b64_tr_b16 v[116:117], v16 offset:0x3200
	ds_read_b64_tr_b16 v[118:119], v16 offset:0x3a00
	ds_read_b64_tr_b16 v[120:121], v16 offset:0x3400
	ds_read_b64_tr_b16 v[122:123], v16 offset:0x3c00
	ds_read_b64_tr_b16 v[124:125], v16 offset:0x3600
	ds_read_b64_tr_b16 v[126:127], v16 offset:0x3e00
	s_waitcnt lgkmcnt(8)
	v_mfma_f32_32x32x16_bf16 v[66:81], v[100:103], v[8:11], v[66:81]
	v_exp_f32_e32 v148, v148
	v_exp_f32_e32 v149, v149
	v_mfma_f32_32x32x16_bf16 v[50:65], v[104:107], v[8:11], v[50:65]
	v_exp_f32_e32 v150, v150
	v_exp_f32_e32 v151, v151
	v_mfma_f32_32x32x16_bf16 v[34:49], v[108:111], v[8:11], v[34:49]
	v_exp_f32_e32 v152, v152
	v_exp_f32_e32 v153, v153
	v_mfma_f32_32x32x16_bf16 v[18:33], v[112:115], v[8:11], v[18:33]
	v_exp_f32_e32 v154, v154
	v_exp_f32_e32 v155, v155
	s_and_b32 s17, s80, 0x6000
	s_add_i32 s17, s17, 0x14000
	v_add_u32_e32 v228, s17, v206
	v_add_u32_e32 v229, s17, v210
	ds_read_b128 v[232:235], v228
	ds_read_b128 v[236:239], v229 offset:4096
	s_waitcnt lgkmcnt(2)
	v_mfma_f32_32x32x16_bf16 v[66:81], v[12:15], v[4:7], v[66:81]
	v_exp_f32_e32 v156, v156
	v_exp_f32_e32 v157, v157
	v_mfma_f32_32x32x16_bf16 v[50:65], v[116:119], v[4:7], v[50:65]
	v_exp_f32_e32 v158, v158
	v_exp_f32_e32 v159, v159
	v_mfma_f32_32x32x16_bf16 v[34:49], v[120:123], v[4:7], v[34:49]
	v_exp_f32_e32 v160, v160
	v_exp_f32_e32 v161, v161
	v_mfma_f32_32x32x16_bf16 v[18:33], v[124:127], v[4:7], v[18:33]
	v_exp_f32_e32 v162, v162
	v_exp_f32_e32 v163, v163
	s_add_i32 s83, s84, 2
	s_cmp_ge_u32 s83, s50
	s_cselect_b64 s[68:69], -1, 0
	s_and_b64 vcc, exec, s[68:69]
	s_cbranch_vccnz .LBB0_948
	s_mul_hi_u32 s6, s13, 0xcccccccd
	s_lshr_b32 s6, s6, 2
	s_mul_i32 s6, s6, 0x14000
	s_sub_i32 s17, s14, s6
	s_min_i32 s6, s83, s49
	s_lshl_b64 s[18:19], s[6:7], 17
	s_add_u32 s20, s52, s18
	s_addc_u32 s21, s53, s19
	s_add_u32 s18, s66, s18
	s_addc_u32 s19, s67, s19
	s_cmp_lg_u32 0, -1
	s_cselect_b32 s6, 0, 0
	s_add_i32 s6, s17, s6
	s_add_i32 s17, s80, 0x4000
	s_and_b32 s17, s17, 0x6000
	s_add_i32 s17, s17, s11
	s_mov_b32 s22, m0
	s_mov_b32 m0, s6
	s_nop 0
	global_load_lds_dwordx4 v194, s[20:21]
	s_mov_b32 m0, s22
	s_add_u32 s20, s20, 0x10000
	s_addc_u32 s21, s21, 0
	s_addk_i32 s6, 0x2000
	s_mov_b32 s22, m0
	s_mov_b32 m0, s6
	s_nop 0
	global_load_lds_dwordx4 v194, s[20:21]
	s_mov_b32 m0, s22
	s_mov_b32 s6, m0
	s_mov_b32 m0, s17
	s_nop 0
	global_load_lds_dwordx4 v195, s[18:19]
	s_mov_b32 m0, s6

.LBB0_950:
	v_add_f32_e32 v16, v3, v184
	s_and_b32 s17, s80, 0x6000
	s_add_i32 s17, s17, 0
	s_add_i32 s17, s17, 0x14000
	s_waitcnt lgkmcnt(1)
	v_mfma_f32_32x32x16_bf16 v[100:115], v[232:235], v[176:179], v[82:97]
	v_add_u32_e32 v3, s17, v207
	ds_read_b128 v[12:15], v3
	v_add_u32_e32 v3, s17, v211
	ds_read_b128 v[216:219], v3 offset:4096
	v_add_f32_e32 v3, 0, v132
	v_add_f32_e32 v3, v133, v3
	v_add_f32_e32 v3, v134, v3
	v_add_f32_e32 v3, v135, v3
	v_cvt_pk_bf16_f32 v180, v132, v133
	v_cvt_pk_bf16_f32 v181, v134, v135
	s_waitcnt lgkmcnt(2)
	v_mfma_f32_32x32x16_bf16 v[116:131], v[236:239], v[176:179], v[82:97]
	v_add_f32_e32 v3, v136, v3
	v_add_f32_e32 v3, v137, v3
	v_add_f32_e32 v3, v138, v3
	v_add_f32_e32 v3, v139, v3
	v_cvt_pk_bf16_f32 v182, v136, v137
	v_cvt_pk_bf16_f32 v183, v138, v139
	s_waitcnt lgkmcnt(1)
	v_mfma_f32_32x32x16_bf16 v[100:115], v[12:15], v[172:175], v[100:115]
	v_add_u32_e32 v4, s17, v208
	v_add_u32_e32 v8, s17, v212
	ds_read_b128 v[4:7], v4
	ds_read_b128 v[220:223], v8 offset:4096
	v_add_f32_e32 v3, v140, v3
	v_add_f32_e32 v3, v141, v3
	v_add_f32_e32 v3, v142, v3
	v_add_f32_e32 v3, v143, v3
	v_cvt_pk_bf16_f32 v12, v140, v141
	v_cvt_pk_bf16_f32 v13, v142, v143
	s_waitcnt lgkmcnt(2)
	v_mfma_f32_32x32x16_bf16 v[116:131], v[216:219], v[172:175], v[116:131]
	v_add_f32_e32 v3, v144, v3
	v_add_f32_e32 v3, v145, v3
	v_add_f32_e32 v3, v146, v3
	v_add_f32_e32 v3, v147, v3
	v_cvt_pk_bf16_f32 v14, v144, v145
	v_cvt_pk_bf16_f32 v15, v146, v147
	s_waitcnt lgkmcnt(1)
	v_mfma_f32_32x32x16_bf16 v[100:115], v[4:7], v[168:171], v[100:115]
	v_add_u32_e32 v8, s17, v209
	v_add_u32_e32 v9, s17, v213
	ds_read_b128 v[216:219], v8
	ds_read_b128 v[224:227], v9 offset:4096
	v_add_f32_e32 v3, v148, v3
	v_add_f32_e32 v3, v149, v3
	v_add_f32_e32 v3, v150, v3
	v_add_f32_e32 v3, v151, v3
	v_cvt_pk_bf16_f32 v8, v148, v149
	v_cvt_pk_bf16_f32 v9, v150, v151
	s_waitcnt lgkmcnt(2)
	v_mfma_f32_32x32x16_bf16 v[116:131], v[220:223], v[168:171], v[116:131]
	v_add_f32_e32 v3, v152, v3
	v_add_f32_e32 v3, v153, v3
	v_add_f32_e32 v3, v154, v3
	v_add_f32_e32 v3, v155, v3
	v_cvt_pk_bf16_f32 v10, v152, v153
	v_cvt_pk_bf16_f32 v11, v154, v155
	s_waitcnt lgkmcnt(1)
	v_mfma_f32_32x32x16_bf16 v[100:115], v[216:219], v[164:167], v[100:115]
	v_add_f32_e32 v3, v156, v3
	v_add_f32_e32 v3, v157, v3
	v_add_f32_e32 v3, v158, v3
	v_add_f32_e32 v3, v159, v3
	v_cvt_pk_bf16_f32 v4, v156, v157
	v_cvt_pk_bf16_f32 v5, v158, v159
	s_waitcnt lgkmcnt(0)
	v_mfma_f32_32x32x16_bf16 v[116:131], v[224:227], v[164:167], v[116:131]
	v_add_f32_e32 v3, v160, v3
	v_add_f32_e32 v3, v161, v3
	v_add_f32_e32 v3, v162, v3
	v_add_f32_e32 v17, v163, v3
	v_cvt_pk_bf16_f32 v6, v160, v161
	v_cvt_pk_bf16_f32 v7, v162, v163
	s_mul_hi_u32 s17, s92, 0xcccccccd
	s_lshr_b32 s17, s17, 2
	s_mul_i32 s17, s17, 0x14000
	v_subrev_u32_e32 v243, s17, v214
	ds_read_b64_tr_b16 v[228:229], v243 offset:0
	ds_read_b64_tr_b16 v[230:231], v243 offset:0x800
	ds_read_b64_tr_b16 v[232:233], v243 offset:0x200
	ds_read_b64_tr_b16 v[234:235], v243 offset:0xa00
	ds_read_b64_tr_b16 v[236:237], v243 offset:0x400
	ds_read_b64_tr_b16 v[238:239], v243 offset:0xc00
	ds_read_b64_tr_b16 v[240:241], v243 offset:0x600
	ds_read_b64_tr_b16 v[242:243], v243 offset:0xe00
	s_nop 0
	v_cmp_ge_f32_e32 vcc, s38, v17
	s_cmp_eq_u64 vcc, exec
	s_cbranch_scc0 .LBB0_960
